# nyq_phase: all 20 row loads requested up front with counted waits (13 of them were single loads each followed by vmcnt(0))
# speedup vs baseline: 1.0018x; 1.0018x over previous
.LBB0_524:
	s_waitcnt lgkmcnt(0)
	v_lshl_add_u64 v[0:1], v[16:17], 0, s[60:61]
	global_load_dwordx4 v[22:25], v[0:1], off offset:-2048
	global_load_dwordx4 v[30:33], v[0:1], off offset:-1024
	global_load_dwordx4 v[4:7], v[0:1], off
	s_nop 0
	global_load_dwordx4 v[0:3], v[0:1], off offset:1024
	s_nop 0
	global_load_dwordx4 v[26:29], v[8:9], off
	global_load_dwordx4 v[34:37], v[8:9], off offset:1024
	global_load_dwordx4 v[40:43], v[8:9], off offset:2048
	global_load_dwordx4 v[48:51], v[8:9], off offset:3072
	global_load_dwordx4 v[52:55], v[10:11], off
	global_load_dwordx4 v[56:59], v[10:11], off offset:1024
	global_load_dwordx4 v[60:63], v[10:11], off offset:2048
	global_load_dwordx4 v[64:67], v[10:11], off offset:3072
	global_load_dwordx4 v[68:71], v[12:13], off
	global_load_dwordx4 v[72:75], v[12:13], off offset:1024
	global_load_dwordx4 v[76:79], v[12:13], off offset:2048
	global_load_dwordx4 v[80:83], v[12:13], off offset:3072
	global_load_dwordx4 v[84:87], v[14:15], off
	global_load_dwordx4 v[88:91], v[14:15], off offset:1024
	global_load_dwordx4 v[92:95], v[14:15], off offset:2048
	global_load_dwordx4 v[96:99], v[14:15], off offset:3072
	s_waitcnt vmcnt(13)
	v_and_b32_e32 v20, 0xffff0000, v22
	v_lshlrev_b32_e32 v18, 16, v22
	v_and_b32_e32 v22, 0xffff0000, v23
	v_and_b32_e32 v38, 0xffff0000, v5
	v_and_b32_e32 v21, 0xffff0000, v26
	v_lshlrev_b32_e32 v19, 16, v26
	v_mul_f32_e32 v21, v20, v21
	v_fmac_f32_e32 v21, v18, v19
	v_lshlrev_b32_e32 v19, 16, v23
	v_and_b32_e32 v23, 0xffff0000, v27
	v_lshlrev_b32_e32 v26, 16, v27
	v_mul_f32_e32 v23, v22, v23
	v_add_f32_e32 v21, 0, v21
	v_fmac_f32_e32 v23, v19, v26
	v_add_f32_e32 v23, v23, v21
	v_lshlrev_b32_e32 v21, 16, v24
	v_and_b32_e32 v24, 0xffff0000, v24
	v_and_b32_e32 v27, 0xffff0000, v28
	v_lshlrev_b32_e32 v26, 16, v28
	v_mul_f32_e32 v27, v24, v27
	v_fmac_f32_e32 v27, v21, v26
	v_add_f32_e32 v26, v27, v23
	v_lshlrev_b32_e32 v23, 16, v25
	v_and_b32_e32 v25, 0xffff0000, v25
	v_and_b32_e32 v28, 0xffff0000, v29
	v_lshlrev_b32_e32 v27, 16, v29
	v_mul_f32_e32 v28, v25, v28
	v_fmac_f32_e32 v28, v23, v27
	v_add_f32_e32 v27, v28, v26
	v_lshlrev_b32_e32 v26, 16, v30
	v_and_b32_e32 v28, 0xffff0000, v30
	v_and_b32_e32 v30, 0xffff0000, v34
	v_lshlrev_b32_e32 v29, 16, v34
	v_mul_f32_e32 v30, v28, v30
	v_fmac_f32_e32 v30, v26, v29
	v_add_f32_e32 v29, v30, v27
	v_lshlrev_b32_e32 v27, 16, v31
	v_and_b32_e32 v30, 0xffff0000, v31
	v_and_b32_e32 v31, 0xffff0000, v35
	v_lshlrev_b32_e32 v34, 16, v35
	v_mul_f32_e32 v31, v30, v31
	v_fmac_f32_e32 v31, v27, v34
	v_add_f32_e32 v31, v31, v29
	v_lshlrev_b32_e32 v29, 16, v32
	v_and_b32_e32 v32, 0xffff0000, v32
	v_and_b32_e32 v35, 0xffff0000, v36
	v_lshlrev_b32_e32 v34, 16, v36
	v_mul_f32_e32 v35, v32, v35
	v_fmac_f32_e32 v35, v29, v34
	v_add_f32_e32 v34, v35, v31
	v_lshlrev_b32_e32 v31, 16, v33
	v_and_b32_e32 v33, 0xffff0000, v33
	v_and_b32_e32 v36, 0xffff0000, v37
	v_lshlrev_b32_e32 v35, 16, v37
	v_mul_f32_e32 v36, v33, v36
	v_fmac_f32_e32 v36, v31, v35
	v_add_f32_e32 v35, v36, v34
	v_lshlrev_b32_e32 v34, 16, v4
	v_and_b32_e32 v36, 0xffff0000, v4
	v_and_b32_e32 v4, 0xffff0000, v40
	v_lshlrev_b32_e32 v37, 16, v40
	v_mul_f32_e32 v4, v36, v4
	v_fmac_f32_e32 v4, v34, v37
	v_add_f32_e32 v4, v4, v35
	v_lshlrev_b32_e32 v35, 16, v5
	v_and_b32_e32 v5, 0xffff0000, v41
	v_lshlrev_b32_e32 v37, 16, v41
	v_mul_f32_e32 v5, v38, v5
	v_fmac_f32_e32 v5, v35, v37
	v_lshlrev_b32_e32 v37, 16, v6
	v_and_b32_e32 v40, 0xffff0000, v6
	v_and_b32_e32 v6, 0xffff0000, v42
	v_add_f32_e32 v4, v5, v4
	v_lshlrev_b32_e32 v5, 16, v42
	v_mul_f32_e32 v6, v40, v6
	v_fmac_f32_e32 v6, v37, v5
	v_add_f32_e32 v4, v6, v4
	v_and_b32_e32 v41, 0xffff0000, v7
	v_and_b32_e32 v6, 0xffff0000, v43
	v_lshlrev_b32_e32 v39, 16, v7
	v_lshlrev_b32_e32 v5, 16, v43
	v_mul_f32_e32 v6, v41, v6
	v_fmac_f32_e32 v6, v39, v5
	v_add_f32_e32 v43, v6, v4
	v_lshlrev_b32_e32 v42, 16, v0
	v_and_b32_e32 v0, 0xffff0000, v0
	s_waitcnt vmcnt(12)
	v_lshlrev_b32_e32 v44, 16, v48
	v_and_b32_e32 v4, 0xffff0000, v48
	v_mul_f32_e32 v4, v0, v4
	v_fmac_f32_e32 v4, v42, v44
	v_add_f32_e32 v43, v4, v43
	v_lshlrev_b32_e32 v4, 16, v1
	v_lshlrev_b32_e32 v44, 16, v49
	v_and_b32_e32 v1, 0xffff0000, v1
	v_and_b32_e32 v5, 0xffff0000, v49
	v_mul_f32_e32 v5, v1, v5
	v_fmac_f32_e32 v5, v4, v44
	v_add_f32_e32 v43, v5, v43
	v_lshlrev_b32_e32 v5, 16, v2
	v_lshlrev_b32_e32 v44, 16, v50
	v_and_b32_e32 v2, 0xffff0000, v2
	v_and_b32_e32 v6, 0xffff0000, v50
	v_mul_f32_e32 v6, v2, v6
	v_fmac_f32_e32 v6, v5, v44
	v_add_f32_e32 v43, v6, v43
	v_lshlrev_b32_e32 v6, 16, v3
	v_lshlrev_b32_e32 v44, 16, v51
	v_and_b32_e32 v3, 0xffff0000, v3
	v_and_b32_e32 v7, 0xffff0000, v51
	v_mul_f32_e32 v7, v3, v7
	v_fmac_f32_e32 v7, v6, v44
	v_add_f32_e32 v7, v7, v43
	v_mbcnt_lo_u32_b32 v43, -1, 0
	v_mbcnt_hi_u32_b32 v43, -1, v43
	s_nop 0
	v_lshlrev_b32_e32 v43, 2, v43
	v_xor_b32_e32 v43, 4, v43
	ds_bpermute_b32 v43, v43, v7
	s_waitcnt lgkmcnt(0)
	v_add_f32_e32 v7, v7, v43
	v_mbcnt_lo_u32_b32 v43, -1, 0
	v_mbcnt_hi_u32_b32 v43, -1, v43
	s_nop 0
	v_lshlrev_b32_e32 v43, 2, v43
	v_xor_b32_e32 v43, 8, v43
	ds_bpermute_b32 v43, v43, v7
	s_waitcnt lgkmcnt(0)
	v_add_f32_e32 v7, v7, v43
	v_mbcnt_lo_u32_b32 v43, -1, 0
	v_mbcnt_hi_u32_b32 v43, -1, v43
	s_nop 0
	v_lshlrev_b32_e32 v43, 2, v43
	v_xor_b32_e32 v43, 16, v43
	ds_bpermute_b32 v43, v43, v7
	s_waitcnt lgkmcnt(0)
	v_add_f32_e32 v7, v7, v43
	v_mbcnt_lo_u32_b32 v43, -1, 0
	v_mbcnt_hi_u32_b32 v43, -1, v43
	s_nop 0
	v_lshlrev_b32_e32 v43, 2, v43
	v_xor_b32_e32 v43, 32, v43
	ds_bpermute_b32 v43, v43, v7
	s_waitcnt lgkmcnt(0)
	v_add_f32_e32 v7, v7, v43
	v_mbcnt_lo_u32_b32 v43, -1, 0
	v_mbcnt_hi_u32_b32 v43, -1, v43
	s_nop 0
	v_lshlrev_b32_e32 v43, 2, v43
	v_xor_b32_e32 v43, 64, v43
	ds_bpermute_b32 v43, v43, v7
	s_waitcnt lgkmcnt(0)
	v_add_f32_e32 v7, v7, v43
	v_mbcnt_lo_u32_b32 v43, -1, 0
	v_mbcnt_hi_u32_b32 v43, -1, v43
	s_nop 0
	v_lshlrev_b32_e32 v43, 2, v43
	v_xor_b32_e32 v43, 0x80, v43
	ds_bpermute_b32 v43, v43, v7
	s_and_saveexec_b64 s[70:71], vcc
	s_cbranch_execz .LBB0_526
	s_add_u32 s2, s0, s60
	s_waitcnt lgkmcnt(0)
	v_add_f32_e32 v7, v7, v43
	s_addc_u32 s3, s1, 0
	v_mov_b32_e32 v43, 0x780000
	global_store_dword v43, v7, s[2:3]
.LBB0_526:
	s_or_b64 exec, exec, s[70:71]
	s_waitcnt vmcnt(12) lgkmcnt(0)
	v_and_b32_e32 v43, 0xffff0000, v52
	v_lshlrev_b32_e32 v7, 16, v52
	v_mul_f32_e32 v43, v20, v43
	v_fmac_f32_e32 v43, v18, v7
	v_and_b32_e32 v44, 0xffff0000, v53
	v_add_f32_e32 v7, 0, v43
	v_lshlrev_b32_e32 v43, 16, v53
	v_mul_f32_e32 v44, v22, v44
	v_fmac_f32_e32 v44, v19, v43
	v_add_f32_e32 v7, v44, v7
	v_and_b32_e32 v44, 0xffff0000, v54
	v_lshlrev_b32_e32 v43, 16, v54
	v_mul_f32_e32 v44, v24, v44
	v_fmac_f32_e32 v44, v21, v43
	v_add_f32_e32 v7, v44, v7
	v_and_b32_e32 v44, 0xffff0000, v55
	v_lshlrev_b32_e32 v43, 16, v55
	v_mul_f32_e32 v44, v25, v44
	v_fmac_f32_e32 v44, v23, v43
	v_add_f32_e32 v7, v44, v7
	s_waitcnt vmcnt(11)
	v_lshlrev_b32_e32 v43, 16, v56
	v_and_b32_e32 v44, 0xffff0000, v56
	v_mul_f32_e32 v44, v28, v44
	v_fmac_f32_e32 v44, v26, v43
	v_add_f32_e32 v7, v44, v7
	v_and_b32_e32 v44, 0xffff0000, v57
	v_lshlrev_b32_e32 v43, 16, v57
	v_mul_f32_e32 v44, v30, v44
	v_fmac_f32_e32 v44, v27, v43
	v_add_f32_e32 v7, v44, v7
	v_and_b32_e32 v44, 0xffff0000, v58
	v_lshlrev_b32_e32 v43, 16, v58
	v_mul_f32_e32 v44, v32, v44
	v_fmac_f32_e32 v44, v29, v43
	v_add_f32_e32 v7, v44, v7
	v_and_b32_e32 v44, 0xffff0000, v59
	v_lshlrev_b32_e32 v43, 16, v59
	v_mul_f32_e32 v44, v33, v44
	v_fmac_f32_e32 v44, v31, v43
	v_add_f32_e32 v7, v44, v7
	s_waitcnt vmcnt(10)
	v_lshlrev_b32_e32 v43, 16, v60
	v_and_b32_e32 v44, 0xffff0000, v60
	v_mul_f32_e32 v44, v36, v44
	v_fmac_f32_e32 v44, v34, v43
	v_add_f32_e32 v7, v44, v7
	v_and_b32_e32 v44, 0xffff0000, v61
	v_lshlrev_b32_e32 v43, 16, v61
	v_mul_f32_e32 v44, v38, v44
	v_fmac_f32_e32 v44, v35, v43
	v_add_f32_e32 v7, v44, v7
	v_and_b32_e32 v44, 0xffff0000, v62
	v_lshlrev_b32_e32 v43, 16, v62
	v_mul_f32_e32 v44, v40, v44
	v_fmac_f32_e32 v44, v37, v43
	v_add_f32_e32 v7, v44, v7
	v_and_b32_e32 v44, 0xffff0000, v63
	v_lshlrev_b32_e32 v43, 16, v63
	v_mul_f32_e32 v44, v41, v44
	v_fmac_f32_e32 v44, v39, v43
	v_add_f32_e32 v7, v44, v7
	s_waitcnt vmcnt(9)
	v_lshlrev_b32_e32 v43, 16, v64
	v_and_b32_e32 v44, 0xffff0000, v64
	v_mul_f32_e32 v44, v0, v44
	v_fmac_f32_e32 v44, v42, v43
	v_add_f32_e32 v7, v44, v7
	v_and_b32_e32 v44, 0xffff0000, v65
	v_lshlrev_b32_e32 v43, 16, v65
	v_mul_f32_e32 v44, v1, v44
	v_fmac_f32_e32 v44, v4, v43
	v_add_f32_e32 v7, v44, v7
	v_and_b32_e32 v44, 0xffff0000, v66
	v_lshlrev_b32_e32 v43, 16, v66
	v_mul_f32_e32 v44, v2, v44
	v_fmac_f32_e32 v44, v5, v43
	v_add_f32_e32 v7, v44, v7
	v_and_b32_e32 v44, 0xffff0000, v67
	v_lshlrev_b32_e32 v43, 16, v67
	v_mul_f32_e32 v44, v3, v44
	v_fmac_f32_e32 v44, v6, v43
	v_mbcnt_lo_u32_b32 v43, -1, 0
	v_mbcnt_hi_u32_b32 v43, -1, v43
	v_add_f32_e32 v7, v44, v7
	v_lshlrev_b32_e32 v43, 2, v43
	v_xor_b32_e32 v43, 4, v43
	ds_bpermute_b32 v43, v43, v7
	s_waitcnt lgkmcnt(0)
	v_add_f32_e32 v7, v7, v43
	v_mbcnt_lo_u32_b32 v43, -1, 0
	v_mbcnt_hi_u32_b32 v43, -1, v43
	s_nop 0
	v_lshlrev_b32_e32 v43, 2, v43
	v_xor_b32_e32 v43, 8, v43
	ds_bpermute_b32 v43, v43, v7
	s_waitcnt lgkmcnt(0)
	v_add_f32_e32 v7, v7, v43
	v_mbcnt_lo_u32_b32 v43, -1, 0
	v_mbcnt_hi_u32_b32 v43, -1, v43
	s_nop 0
	v_lshlrev_b32_e32 v43, 2, v43
	v_xor_b32_e32 v43, 16, v43
	ds_bpermute_b32 v43, v43, v7
	s_waitcnt lgkmcnt(0)
	v_add_f32_e32 v7, v7, v43
	v_mbcnt_lo_u32_b32 v43, -1, 0
	v_mbcnt_hi_u32_b32 v43, -1, v43
	s_nop 0
	v_lshlrev_b32_e32 v43, 2, v43
	v_xor_b32_e32 v43, 32, v43
	ds_bpermute_b32 v43, v43, v7
	s_waitcnt lgkmcnt(0)
	v_add_f32_e32 v7, v7, v43
	v_mbcnt_lo_u32_b32 v43, -1, 0
	v_mbcnt_hi_u32_b32 v43, -1, v43
	s_nop 0
	v_lshlrev_b32_e32 v43, 2, v43
	v_xor_b32_e32 v43, 64, v43
	ds_bpermute_b32 v43, v43, v7
	s_waitcnt lgkmcnt(0)
	v_add_f32_e32 v7, v7, v43
	v_mbcnt_lo_u32_b32 v43, -1, 0
	v_mbcnt_hi_u32_b32 v43, -1, v43
	s_nop 0
	v_lshlrev_b32_e32 v43, 2, v43
	v_xor_b32_e32 v43, 0x80, v43
	ds_bpermute_b32 v43, v43, v7
	s_and_saveexec_b64 s[70:71], vcc
	s_cbranch_execz .LBB0_528
	s_add_u32 s2, s0, s60
	s_waitcnt lgkmcnt(0)
	v_add_f32_e32 v7, v7, v43
	s_addc_u32 s3, s1, 0
	v_mov_b32_e32 v43, 0x781000
	global_store_dword v43, v7, s[2:3]
.LBB0_528:
	s_or_b64 exec, exec, s[70:71]
	s_waitcnt vmcnt(9) lgkmcnt(0)
	v_and_b32_e32 v43, 0xffff0000, v68
	v_lshlrev_b32_e32 v7, 16, v68
	v_mul_f32_e32 v43, v20, v43
	v_fmac_f32_e32 v43, v18, v7
	v_and_b32_e32 v44, 0xffff0000, v69
	v_add_f32_e32 v7, 0, v43
	v_lshlrev_b32_e32 v43, 16, v69
	v_mul_f32_e32 v44, v22, v44
	v_fmac_f32_e32 v44, v19, v43
	v_add_f32_e32 v7, v44, v7
	v_and_b32_e32 v44, 0xffff0000, v70
	v_lshlrev_b32_e32 v43, 16, v70
	v_mul_f32_e32 v44, v24, v44
	v_fmac_f32_e32 v44, v21, v43
	v_add_f32_e32 v7, v44, v7
	v_and_b32_e32 v44, 0xffff0000, v71
	v_lshlrev_b32_e32 v43, 16, v71
	v_mul_f32_e32 v44, v25, v44
	v_fmac_f32_e32 v44, v23, v43
	v_add_f32_e32 v7, v44, v7
	s_waitcnt vmcnt(8)
	v_lshlrev_b32_e32 v43, 16, v72
	v_and_b32_e32 v44, 0xffff0000, v72
	v_mul_f32_e32 v44, v28, v44
	v_fmac_f32_e32 v44, v26, v43
	v_add_f32_e32 v7, v44, v7
	v_and_b32_e32 v44, 0xffff0000, v73
	v_lshlrev_b32_e32 v43, 16, v73
	v_mul_f32_e32 v44, v30, v44
	v_fmac_f32_e32 v44, v27, v43
	v_add_f32_e32 v7, v44, v7
	v_and_b32_e32 v44, 0xffff0000, v74
	v_lshlrev_b32_e32 v43, 16, v74
	v_mul_f32_e32 v44, v32, v44
	v_fmac_f32_e32 v44, v29, v43
	v_add_f32_e32 v7, v44, v7
	v_and_b32_e32 v44, 0xffff0000, v75
	v_lshlrev_b32_e32 v43, 16, v75
	v_mul_f32_e32 v44, v33, v44
	v_fmac_f32_e32 v44, v31, v43
	v_add_f32_e32 v7, v44, v7
	s_waitcnt vmcnt(7)
; __device__ __forceinline__ void nyq_phase(const bf16* H, const bf16* WfT, float* nyq, int gw, int NGW, int lane) {
;     ...
;         for (int b = 0; b < 4; ++b) { const v4u* hp = (const v4u*)(H + (size_t)(b * SEQ + SEQ / 2) * DM) + lane; float s = 0.f;
; #pragma unroll
;             for (int j = 0; j < 4; ++j) { const v4u hv = hp[64 * j];
; #pragma unroll
;                 for (int e = 0; e < 4; ++e) s += bflo(wv[j][e]) * bflo(hv[e]) + bfhi(wv[j][e]) * bfhi(hv[e]); }
;             s = wave_sum(s); if (lane == 0) nyq[b * 1024 + ch] = s; }
	v_lshlrev_b32_e32 v43, 16, v76
	v_and_b32_e32 v44, 0xffff0000, v76
	v_mul_f32_e32 v44, v36, v44
	v_fmac_f32_e32 v44, v34, v43
	v_add_f32_e32 v7, v44, v7
	v_and_b32_e32 v44, 0xffff0000, v77
	v_lshlrev_b32_e32 v43, 16, v77
	v_mul_f32_e32 v44, v38, v44
	v_fmac_f32_e32 v44, v35, v43
	v_add_f32_e32 v7, v44, v7
	v_and_b32_e32 v44, 0xffff0000, v78
	v_lshlrev_b32_e32 v43, 16, v78
	v_mul_f32_e32 v44, v40, v44
	v_fmac_f32_e32 v44, v37, v43
	v_add_f32_e32 v7, v44, v7
	v_and_b32_e32 v44, 0xffff0000, v79
	v_lshlrev_b32_e32 v43, 16, v79
	v_mul_f32_e32 v44, v41, v44
	v_fmac_f32_e32 v44, v39, v43
	v_add_f32_e32 v7, v44, v7
	s_waitcnt vmcnt(6)
	v_lshlrev_b32_e32 v43, 16, v80
	v_and_b32_e32 v44, 0xffff0000, v80
	v_mul_f32_e32 v44, v0, v44
	v_fmac_f32_e32 v44, v42, v43
	v_add_f32_e32 v7, v44, v7
	v_and_b32_e32 v44, 0xffff0000, v81
	v_lshlrev_b32_e32 v43, 16, v81
	v_mul_f32_e32 v44, v1, v44
	v_fmac_f32_e32 v44, v4, v43
	v_add_f32_e32 v7, v44, v7
	v_and_b32_e32 v44, 0xffff0000, v82
	v_lshlrev_b32_e32 v43, 16, v82
	v_mul_f32_e32 v44, v2, v44
	v_fmac_f32_e32 v44, v5, v43
	v_add_f32_e32 v7, v44, v7
	v_and_b32_e32 v44, 0xffff0000, v83
	v_lshlrev_b32_e32 v43, 16, v83
	v_mul_f32_e32 v44, v3, v44
	v_fmac_f32_e32 v44, v6, v43
	v_mbcnt_lo_u32_b32 v43, -1, 0
	v_mbcnt_hi_u32_b32 v43, -1, v43
	v_add_f32_e32 v7, v44, v7
	v_lshlrev_b32_e32 v43, 2, v43
	v_xor_b32_e32 v43, 4, v43
	ds_bpermute_b32 v43, v43, v7
	s_waitcnt lgkmcnt(0)
	v_add_f32_e32 v7, v7, v43
	v_mbcnt_lo_u32_b32 v43, -1, 0
	v_mbcnt_hi_u32_b32 v43, -1, v43
	s_nop 0
	v_lshlrev_b32_e32 v43, 2, v43
	v_xor_b32_e32 v43, 8, v43
	ds_bpermute_b32 v43, v43, v7
	s_waitcnt lgkmcnt(0)
	v_add_f32_e32 v7, v7, v43
	v_mbcnt_lo_u32_b32 v43, -1, 0
	v_mbcnt_hi_u32_b32 v43, -1, v43
	s_nop 0
	v_lshlrev_b32_e32 v43, 2, v43
	v_xor_b32_e32 v43, 16, v43
	ds_bpermute_b32 v43, v43, v7
	s_waitcnt lgkmcnt(0)
	v_add_f32_e32 v7, v7, v43
	v_mbcnt_lo_u32_b32 v43, -1, 0
	v_mbcnt_hi_u32_b32 v43, -1, v43
	s_nop 0
	v_lshlrev_b32_e32 v43, 2, v43
	v_xor_b32_e32 v43, 32, v43
	ds_bpermute_b32 v43, v43, v7
	s_waitcnt lgkmcnt(0)
	v_add_f32_e32 v7, v7, v43
	v_mbcnt_lo_u32_b32 v43, -1, 0
	v_mbcnt_hi_u32_b32 v43, -1, v43
	s_nop 0
	v_lshlrev_b32_e32 v43, 2, v43
	v_xor_b32_e32 v43, 64, v43
	ds_bpermute_b32 v43, v43, v7
	s_waitcnt lgkmcnt(0)
	v_add_f32_e32 v7, v7, v43
	v_mbcnt_lo_u32_b32 v43, -1, 0
	v_mbcnt_hi_u32_b32 v43, -1, v43
	s_nop 0
	v_lshlrev_b32_e32 v43, 2, v43
	v_xor_b32_e32 v43, 0x80, v43
	ds_bpermute_b32 v43, v43, v7
	s_and_saveexec_b64 s[70:71], vcc
	s_cbranch_execz .LBB0_530
	s_add_u32 s2, s0, s60
	s_waitcnt lgkmcnt(0)
	v_add_f32_e32 v7, v7, v43
	s_addc_u32 s3, s1, 0
	v_mov_b32_e32 v43, 0x782000
	global_store_dword v43, v7, s[2:3]
.LBB0_530:
	s_or_b64 exec, exec, s[70:71]
	s_waitcnt vmcnt(6) lgkmcnt(0)
	v_and_b32_e32 v43, 0xffff0000, v84
	v_lshlrev_b32_e32 v7, 16, v84
	v_mul_f32_e32 v20, v20, v43
	v_fmac_f32_e32 v20, v18, v7
	v_add_f32_e32 v7, 0, v20
	v_and_b32_e32 v20, 0xffff0000, v85
	v_lshlrev_b32_e32 v18, 16, v85
	v_mul_f32_e32 v20, v22, v20
	v_fmac_f32_e32 v20, v19, v18
	v_and_b32_e32 v19, 0xffff0000, v86
	v_lshlrev_b32_e32 v18, 16, v86
	v_mul_f32_e32 v19, v24, v19
	v_add_f32_e32 v7, v20, v7
	v_fmac_f32_e32 v19, v21, v18
	v_add_f32_e32 v7, v19, v7
	v_and_b32_e32 v19, 0xffff0000, v87
	v_lshlrev_b32_e32 v18, 16, v87
	v_mul_f32_e32 v19, v25, v19
	v_fmac_f32_e32 v19, v23, v18
	v_add_f32_e32 v7, v19, v7
	s_waitcnt vmcnt(5)
	v_lshlrev_b32_e32 v22, 16, v88
	v_and_b32_e32 v18, 0xffff0000, v88
	v_mul_f32_e32 v18, v28, v18
	v_fmac_f32_e32 v18, v26, v22
	v_add_f32_e32 v7, v18, v7
	v_lshlrev_b32_e32 v18, 16, v89
	v_and_b32_e32 v19, 0xffff0000, v89
	v_mul_f32_e32 v19, v30, v19
	v_fmac_f32_e32 v19, v27, v18
	v_add_f32_e32 v7, v19, v7
	v_and_b32_e32 v19, 0xffff0000, v90
	v_lshlrev_b32_e32 v18, 16, v90
	v_mul_f32_e32 v19, v32, v19
	v_fmac_f32_e32 v19, v29, v18
	v_add_f32_e32 v7, v19, v7
	v_and_b32_e32 v19, 0xffff0000, v91
	v_lshlrev_b32_e32 v18, 16, v91
	v_mul_f32_e32 v19, v33, v19
	v_fmac_f32_e32 v19, v31, v18
	v_add_f32_e32 v7, v19, v7
	s_waitcnt vmcnt(4)
	v_lshlrev_b32_e32 v22, 16, v92
	v_and_b32_e32 v18, 0xffff0000, v92
	v_mul_f32_e32 v18, v36, v18
	v_fmac_f32_e32 v18, v34, v22
	v_add_f32_e32 v7, v18, v7
	v_lshlrev_b32_e32 v18, 16, v93
	v_and_b32_e32 v19, 0xffff0000, v93
	v_mul_f32_e32 v19, v38, v19
	v_fmac_f32_e32 v19, v35, v18
	v_add_f32_e32 v7, v19, v7
	v_and_b32_e32 v19, 0xffff0000, v94
	v_lshlrev_b32_e32 v18, 16, v94
	v_mul_f32_e32 v19, v40, v19
	v_fmac_f32_e32 v19, v37, v18
	v_add_f32_e32 v7, v19, v7
	v_and_b32_e32 v19, 0xffff0000, v95
	v_lshlrev_b32_e32 v18, 16, v95
	v_mul_f32_e32 v19, v41, v19
	v_fmac_f32_e32 v19, v39, v18
	v_add_f32_e32 v7, v19, v7
	s_waitcnt vmcnt(3)
	v_lshlrev_b32_e32 v22, 16, v96
	v_and_b32_e32 v18, 0xffff0000, v96
	v_mul_f32_e32 v0, v0, v18
	v_fmac_f32_e32 v0, v42, v22
	v_and_b32_e32 v18, 0xffff0000, v97
	v_add_f32_e32 v0, v0, v7
	v_lshlrev_b32_e32 v7, 16, v97
	v_mul_f32_e32 v1, v1, v18
	v_fmac_f32_e32 v1, v4, v7
	v_and_b32_e32 v4, 0xffff0000, v98
	v_add_f32_e32 v0, v1, v0
	v_lshlrev_b32_e32 v1, 16, v98
	v_mul_f32_e32 v2, v2, v4
	v_fmac_f32_e32 v2, v5, v1
	v_add_f32_e32 v0, v2, v0
	v_and_b32_e32 v2, 0xffff0000, v99
	v_lshlrev_b32_e32 v1, 16, v99
	v_mul_f32_e32 v2, v3, v2
	v_fmac_f32_e32 v2, v6, v1
	v_mbcnt_lo_u32_b32 v1, -1, 0
	v_mbcnt_hi_u32_b32 v1, -1, v1
	v_add_f32_e32 v0, v2, v0
	v_lshlrev_b32_e32 v1, 2, v1
	v_xor_b32_e32 v1, 4, v1
	ds_bpermute_b32 v1, v1, v0
	s_waitcnt lgkmcnt(0)
	v_add_f32_e32 v0, v0, v1
	v_mbcnt_lo_u32_b32 v1, -1, 0
	v_mbcnt_hi_u32_b32 v1, -1, v1
	s_nop 0
	v_lshlrev_b32_e32 v1, 2, v1
	v_xor_b32_e32 v1, 8, v1
	ds_bpermute_b32 v1, v1, v0
	s_waitcnt lgkmcnt(0)
	v_add_f32_e32 v0, v0, v1
	v_mbcnt_lo_u32_b32 v1, -1, 0
	v_mbcnt_hi_u32_b32 v1, -1, v1
	s_nop 0
	v_lshlrev_b32_e32 v1, 2, v1
	v_xor_b32_e32 v1, 16, v1
	ds_bpermute_b32 v1, v1, v0
	s_waitcnt lgkmcnt(0)
	v_add_f32_e32 v0, v0, v1
	v_mbcnt_lo_u32_b32 v1, -1, 0
	v_mbcnt_hi_u32_b32 v1, -1, v1
	s_nop 0
	v_lshlrev_b32_e32 v1, 2, v1
	v_xor_b32_e32 v1, 32, v1
	ds_bpermute_b32 v1, v1, v0
	s_waitcnt lgkmcnt(0)
	v_add_f32_e32 v0, v0, v1
	v_mbcnt_lo_u32_b32 v1, -1, 0
	v_mbcnt_hi_u32_b32 v1, -1, v1
	s_nop 0
	v_lshlrev_b32_e32 v1, 2, v1
	v_xor_b32_e32 v1, 64, v1
	ds_bpermute_b32 v1, v1, v0
	s_waitcnt lgkmcnt(0)
	v_add_f32_e32 v0, v0, v1
	v_mbcnt_lo_u32_b32 v1, -1, 0
	v_mbcnt_hi_u32_b32 v1, -1, v1
	s_nop 0
	v_lshlrev_b32_e32 v1, 2, v1
	v_xor_b32_e32 v1, 0x80, v1
	ds_bpermute_b32 v1, v1, v0
	s_and_saveexec_b64 s[70:71], vcc
	s_cbranch_execz .LBB0_523
	s_add_u32 s2, s0, s60
	s_waitcnt lgkmcnt(0)
	v_add_f32_e32 v0, v0, v1
	s_addc_u32 s3, s1, 0
	v_mov_b32_e32 v1, 0x783000
	global_store_dword v1, v0, s[2:3]
	s_branch .LBB0_523
